# P6 sample-row GEMM: each wave takes 1/8 of K and accumulates both tiles from one copy of the weight fragments
# speedup vs baseline: 1.0133x; 1.0026x over previous
; #define LAS __attribute__((address_space(3)))
; __device__ __forceinline__ f32x4 mfma16(h16x8 a, h16x8 b, f32x4 c) { return __builtin_amdgcn_mfma_f32_16x16x32_f16(a, b, c, 0, 0, 0); }
; __device__ __forceinline__ void skinny_down_splitk(const Params& p, LAS unsigned char* lds) {
;     ...
;         const h16* ap = A + (size_t)(MP + rt * 16 + fr) * DFF + ksp * 1024 + fq * 8;
;         const h16* bp = Bt + (size_t)(ct * 16 + fr) * DFF + ksp * 1024 + fq * 8;
;         f32x4 acc = {0.f, 0.f, 0.f, 0.f};
; #pragma unroll 8
;         for (int k = 0; k < 1024; k += 32) { const h16x8 a = *(const h16x8*)(ap + k); const h16x8 b = *(const h16x8*)(bp + k); acc = mfma16(b, a, acc); }
;         *(LAS f32x4*)(RED + ((grp * 4 + ksp) * 64 + lane) * 4) = acc;
.LBB0_614:
	s_cmpk_lg_i32 s33, 0x100
	s_cbranch_scc1 .Lsk6_orig
	v_lshrrev_b32_e32 v22, 6, v132
	v_mov_b32_e32 v140, 0
	v_readfirstlane_b32 s97, v22
	v_mov_b32_e32 v141, 0
	s_lshr_b32 s98, s97, 2
	s_and_b32 s99, s97, 3
	s_lshl_b32 s98, s98, 12
	s_lshl_b32 s99, s99, 10
	s_sub_i32 s98, s98, s99
	s_addk_i32 s98, 0xff00
	s_ashr_i32 s99, s98, 31
	v_mov_b32_e32 v22, s99
	v_add_co_u32_e64 v10, s[100:101], s98, v10
	v_mov_b32_e32 v142, 0
	v_mov_b32_e32 v143, 0
	v_addc_co_u32_e64 v11, s[100:101], v22, v11, s[100:101]
	v_add_co_u32_e64 v12, s[100:101], s98, v12
	s_mov_b32 s98, 0xfffe0000
	s_cmp_lt_u32 s97, 4
	s_cselect_b32 s98, 0x20000, s98
	v_addc_co_u32_e64 v13, s[100:101], v22, v13, s[100:101]
	s_cselect_b32 s99, 0, -1
	v_mov_b32_e32 v23, s99
	v_add_co_u32_e64 v22, s[100:101], s98, v12
	s_nop 1
	v_addc_co_u32_e64 v23, s[100:101], v23, v13, s[100:101]
	global_load_dwordx4 v[24:27], v[10:11], off
	global_load_dwordx4 v[28:31], v[12:13], off
	global_load_dwordx4 v[32:35], v[22:23], off
	global_load_dwordx4 v[36:39], v[10:11], off offset:64
	global_load_dwordx4 v[40:43], v[12:13], off offset:64
	global_load_dwordx4 v[44:47], v[22:23], off offset:64
	global_load_dwordx4 v[48:51], v[10:11], off offset:128
	global_load_dwordx4 v[52:55], v[12:13], off offset:128
	global_load_dwordx4 v[56:59], v[22:23], off offset:128
	global_load_dwordx4 v[60:63], v[10:11], off offset:192
	global_load_dwordx4 v[64:67], v[12:13], off offset:192
	global_load_dwordx4 v[68:71], v[22:23], off offset:192
	global_load_dwordx4 v[72:75], v[10:11], off offset:256
	global_load_dwordx4 v[76:79], v[12:13], off offset:256
	global_load_dwordx4 v[80:83], v[22:23], off offset:256
	global_load_dwordx4 v[84:87], v[10:11], off offset:320
	global_load_dwordx4 v[88:91], v[12:13], off offset:320
	global_load_dwordx4 v[92:95], v[22:23], off offset:320
	global_load_dwordx4 v[96:99], v[10:11], off offset:384
	global_load_dwordx4 v[100:103], v[12:13], off offset:384
	global_load_dwordx4 v[104:107], v[22:23], off offset:384
	global_load_dwordx4 v[108:111], v[10:11], off offset:448
	global_load_dwordx4 v[112:115], v[12:13], off offset:448
	global_load_dwordx4 v[116:119], v[22:23], off offset:448
	global_load_dwordx4 v[120:123], v[10:11], off offset:512
	global_load_dwordx4 v[124:127], v[12:13], off offset:512
	global_load_dwordx4 v[148:151], v[22:23], off offset:512
	global_load_dwordx4 v[152:155], v[10:11], off offset:576
	global_load_dwordx4 v[156:159], v[12:13], off offset:576
	global_load_dwordx4 v[160:163], v[22:23], off offset:576
	global_load_dwordx4 v[164:167], v[10:11], off offset:640
	global_load_dwordx4 v[168:171], v[12:13], off offset:640
	global_load_dwordx4 v[172:175], v[22:23], off offset:640
	global_load_dwordx4 v[176:179], v[10:11], off offset:704
	global_load_dwordx4 v[180:183], v[12:13], off offset:704
	global_load_dwordx4 v[184:187], v[22:23], off offset:704
	global_load_dwordx4 v[188:191], v[10:11], off offset:768
	global_load_dwordx4 v[192:195], v[12:13], off offset:768
	global_load_dwordx4 v[196:199], v[22:23], off offset:768
	global_load_dwordx4 v[200:203], v[10:11], off offset:832
	global_load_dwordx4 v[204:207], v[12:13], off offset:832
	global_load_dwordx4 v[208:211], v[22:23], off offset:832
	global_load_dwordx4 v[212:215], v[10:11], off offset:896
	global_load_dwordx4 v[216:219], v[12:13], off offset:896
	global_load_dwordx4 v[220:223], v[22:23], off offset:896
	global_load_dwordx4 v[224:227], v[10:11], off offset:960
	global_load_dwordx4 v[228:231], v[12:13], off offset:960
	global_load_dwordx4 v[232:235], v[22:23], off offset:960
	s_waitcnt vmcnt(45)
	v_mfma_f32_16x16x32_f16 v[0:3], v[24:27], v[28:31], v[0:3]
	v_mfma_f32_16x16x32_f16 v[140:143], v[24:27], v[32:35], v[140:143]
	s_waitcnt vmcnt(42)
	v_mfma_f32_16x16x32_f16 v[0:3], v[36:39], v[40:43], v[0:3]
	v_mfma_f32_16x16x32_f16 v[140:143], v[36:39], v[44:47], v[140:143]
	s_waitcnt vmcnt(39)
	v_mfma_f32_16x16x32_f16 v[0:3], v[48:51], v[52:55], v[0:3]
	v_mfma_f32_16x16x32_f16 v[140:143], v[48:51], v[56:59], v[140:143]
	s_waitcnt vmcnt(36)
	v_mfma_f32_16x16x32_f16 v[0:3], v[60:63], v[64:67], v[0:3]
	v_mfma_f32_16x16x32_f16 v[140:143], v[60:63], v[68:71], v[140:143]
	s_waitcnt vmcnt(33)
	v_mfma_f32_16x16x32_f16 v[0:3], v[72:75], v[76:79], v[0:3]
	v_mfma_f32_16x16x32_f16 v[140:143], v[72:75], v[80:83], v[140:143]
	s_waitcnt vmcnt(30)
	v_mfma_f32_16x16x32_f16 v[0:3], v[84:87], v[88:91], v[0:3]
	v_mfma_f32_16x16x32_f16 v[140:143], v[84:87], v[92:95], v[140:143]
	s_waitcnt vmcnt(27)
	v_mfma_f32_16x16x32_f16 v[0:3], v[96:99], v[100:103], v[0:3]
	v_mfma_f32_16x16x32_f16 v[140:143], v[96:99], v[104:107], v[140:143]
	s_waitcnt vmcnt(24)
	v_mfma_f32_16x16x32_f16 v[0:3], v[108:111], v[112:115], v[0:3]
	v_mfma_f32_16x16x32_f16 v[140:143], v[108:111], v[116:119], v[140:143]
	s_waitcnt vmcnt(21)
	v_mfma_f32_16x16x32_f16 v[0:3], v[120:123], v[124:127], v[0:3]
	v_mfma_f32_16x16x32_f16 v[140:143], v[120:123], v[148:151], v[140:143]
	s_waitcnt vmcnt(18)
	v_mfma_f32_16x16x32_f16 v[0:3], v[152:155], v[156:159], v[0:3]
	v_mfma_f32_16x16x32_f16 v[140:143], v[152:155], v[160:163], v[140:143]
	s_waitcnt vmcnt(15)
	v_mfma_f32_16x16x32_f16 v[0:3], v[164:167], v[168:171], v[0:3]
	v_mfma_f32_16x16x32_f16 v[140:143], v[164:167], v[172:175], v[140:143]
	s_waitcnt vmcnt(12)
	v_mfma_f32_16x16x32_f16 v[0:3], v[176:179], v[180:183], v[0:3]
	v_mfma_f32_16x16x32_f16 v[140:143], v[176:179], v[184:187], v[140:143]
	s_waitcnt vmcnt(9)
	v_mfma_f32_16x16x32_f16 v[0:3], v[188:191], v[192:195], v[0:3]
	v_mfma_f32_16x16x32_f16 v[140:143], v[188:191], v[196:199], v[140:143]
	s_waitcnt vmcnt(6)
	v_mfma_f32_16x16x32_f16 v[0:3], v[200:203], v[204:207], v[0:3]
	v_mfma_f32_16x16x32_f16 v[140:143], v[200:203], v[208:211], v[140:143]
	s_waitcnt vmcnt(3)
	v_mfma_f32_16x16x32_f16 v[0:3], v[212:215], v[216:219], v[0:3]
	v_mfma_f32_16x16x32_f16 v[140:143], v[212:215], v[220:223], v[140:143]
	s_waitcnt vmcnt(0)
	v_mfma_f32_16x16x32_f16 v[0:3], v[224:227], v[228:231], v[0:3]
	v_mfma_f32_16x16x32_f16 v[140:143], v[224:227], v[232:235], v[140:143]
	v_and_b32_e32 v24, 63, v132
	v_lshlrev_b32_e32 v24, 4, v24
	s_lshl_b32 s98, s97, 10
	s_xor_b32 s99, s98, 0x1000
	v_add_u32_e32 v25, s98, v24
	v_add_u32_e32 v24, s99, v24
	s_nop 7
	s_nop 3
	ds_write_b128 v25, v[140:143] offset:8192
	s_waitcnt lgkmcnt(0)
	s_barrier
	ds_read_b128 v[28:31], v24 offset:8192
	s_waitcnt lgkmcnt(0)
	v_pk_add_f32 v[0:1], v[0:1], v[28:29]
	v_pk_add_f32 v[2:3], v[2:3], v[30:31]
	s_branch .Lsk6_done

; #define LAS __attribute__((address_space(3)))
; __device__ __forceinline__ void skinny_down_splitk(const Params& p, LAS unsigned char* lds) {
;     ...
;         *(LAS f32x4*)(RED + ((grp * 4 + ksp) * 64 + lane) * 4) = acc;
;         __syncthreads();
;         if (ksp == 0 && act) {
; #pragma unroll
;             for (int q = 1; q < 4; ++q) acc += *(const LAS f32x4*)(RED + ((grp * 4 + q) * 64 + lane) * 4);
;             const int row = MP + rt * 16 + fr, col = ct * 16 + fq * 4, sidx = row - MP;
;             f32x4 v = acc + *(const f32x4*)((const float*)(ws + OFF_X1) + (size_t)row * D + col);
;             *(f32x4*)(p.out + O_YS + (size_t)sidx * D + col) = v;
;             float ss = v[0] * v[0] + v[1] * v[1] + v[2] * v[2] + v[3] * v[3];
;             ss += __shfl_xor(ss, 16); ss += __shfl_xor(ss, 32);
;             if (fq == 0) atomicAdd((float*)(ws + OFF_SS2) + row, ss);
;         }
.Lsk6_done:
	s_and_b64 s[0:1], vcc, s[0:1]
	s_nop 5
	ds_write_b128 v16, v[0:3]
	s_waitcnt lgkmcnt(0)
	s_barrier
	s_and_saveexec_b64 s[8:9], s[0:1]
	s_cbranch_execz .LBB0_608
	v_or_b32_e32 v10, v21, v15
	v_lshlrev_b64 v[12:13], 12, v[4:5]
	v_ashrrev_i32_e32 v11, 31, v10
	v_lshl_add_u64 v[12:13], s[86:87], 0, v[12:13]
	v_lshlrev_b64 v[34:35], 2, v[10:11]
	v_lshl_add_u64 v[10:11], v[12:13], 0, v[34:35]
	global_load_dwordx4 v[10:13], v[10:11], off
	ds_read_b128 v[22:25], v17 offset:1024
	ds_read_b128 v[26:29], v17 offset:2048
	ds_read_b128 v[30:33], v17 offset:3072
	v_cmp_lt_i32_e64 s[0:1], v19, v135
	v_ashrrev_i32_e32 v37, 31, v4
	s_waitcnt lgkmcnt(2)
	v_pk_add_f32 v[0:1], v[0:1], v[22:23]
	v_pk_add_f32 v[2:3], v[2:3], v[24:25]
	s_waitcnt lgkmcnt(1)
	v_pk_add_f32 v[0:1], v[0:1], v[26:27]
	v_pk_add_f32 v[2:3], v[2:3], v[28:29]
	s_waitcnt lgkmcnt(0)
	v_pk_add_f32 v[0:1], v[0:1], v[30:31]
	v_pk_add_f32 v[2:3], v[2:3], v[32:33]
	v_cndmask_b32_e64 v21, v129, v19, s[0:1]
	v_lshlrev_b32_e32 v21, 2, v21
	v_mov_b32_e32 v36, v4
	v_cmp_lt_i32_e64 s[0:1], v20, v135
	s_waitcnt vmcnt(0)
	v_pk_add_f32 v[10:11], v[0:1], v[10:11]
	s_nop 0
	v_mul_f32_e32 v22, v11, v11
	v_pk_add_f32 v[12:13], v[2:3], v[12:13]
	v_fmac_f32_e32 v22, v10, v10
	v_fmac_f32_e32 v22, v12, v12
	v_fmac_f32_e32 v22, v13, v13
	ds_bpermute_b32 v21, v21, v22
	v_lshlrev_b64 v[0:1], 12, v[36:37]
	v_cndmask_b32_e64 v38, v129, v20, s[0:1]
	v_lshl_add_u64 v[0:1], s[4:5], 0, v[0:1]
	v_lshlrev_b32_e32 v23, 2, v38
	v_lshl_add_u64 v[2:3], v[0:1], 0, v[34:35]
	s_waitcnt lgkmcnt(0)
	v_add_f32_e32 v0, v22, v21
	ds_bpermute_b32 v1, v23, v0
	v_add_co_u32_e64 v2, s[0:1], s13, v2
	s_nop 1
	v_addc_co_u32_e64 v3, s[0:1], -1, v3, s[0:1]
	global_store_dwordx4 v[2:3], v[10:13], off
	s_and_b64 exec, exec, s[2:3]
	s_cbranch_execz .LBB0_608
	s_waitcnt lgkmcnt(0)
	v_add_f32_e32 v2, v0, v1
	v_lshl_add_u64 v[0:1], v[4:5], 2, s[14:15]
	global_atomic_add_f32 v[0:1], v2, off
	s_branch .LBB0_608
